# v97: v96 + K-loop waits relaxed to vmcnt(9) in the super-phases whose window holds a parked store
# speedup vs baseline: 1.0056x; 1.0024x over previous
.LBB0_182:
	v_lshlrev_b32_e32 v13, 1, v12
	v_lshlrev_b32_e32 v15, 2, v139
	s_lshl_b32 s69, s16, 6
	v_lshl_or_b32 v14, v139, 6, v13
	s_lshl_b32 s16, s16, 13
	v_and_b32_e32 v15, 32, v15
	v_bitop3_b32 v14, v14, s16, v15 bitop3:0xde
	s_mov_b64 s[16:17], 0x80
	s_sext_i32_i16 s94, s6
	s_and_b32 s6, s7, 3
	s_add_i32 m0, s64, 0x18000
	v_lshl_add_u64 v[6:7], v[6:7], 0, s[16:17]
	s_lshl_b32 s24, s6, 5
	s_lshl_b32 s22, s6, 12
	s_waitcnt vmcnt(2)
	s_barrier
	global_load_lds_dwordx4 v[6:7], off
	v_lshl_add_u64 v[2:3], v[2:3], 0, s[16:17]
	s_add_i32 m0, s64, 0x1a000
	s_add_i32 s70, s64, 0x8000
	s_add_i32 s71, s64, 0xa000
	global_load_lds_dwordx4 v[2:3], off
	v_lshl_add_u64 v[0:1], v[0:1], 0, s[16:17]
	s_mov_b32 m0, s70
	s_add_u32 s20, s56, 0x40080
	global_load_lds_dwordx4 v[0:1], off
	v_lshl_add_u64 v[0:1], v[4:5], 0, s[16:17]
	s_mov_b32 m0, s71
	s_addc_u32 s21, s57, 0
	global_load_lds_dwordx4 v[0:1], off
	s_add_i32 m0, s64, 0x1c000
	v_lshl_add_u64 v[0:1], s[20:21], 0, v[132:133]
	global_load_lds_dwordx4 v[0:1], off
	v_lshl_add_u64 v[0:1], s[20:21], 0, v[128:129]
	s_add_i32 m0, s64, 0x1e000
	v_lshlrev_b32_e32 v15, 6, v158
	global_load_lds_dwordx4 v[0:1], off
	s_movk_i32 s19, 0x3c0
	v_lshlrev_b32_e32 v1, 2, v158
	v_and_or_b32 v0, v15, s19, v13
	v_and_b32_e32 v1, 32, v1
	v_lshlrev_b32_e32 v136, 2, v12
	v_bitop3_b32 v159, s22, v0, v1 bitop3:0xf6
	s_cmpk_lt_u32 s18, 0x100
	v_lshl_add_u64 v[0:1], s[10:11], 0, v[136:137]
	s_mov_b64 s[22:23], 0x500000
	s_cselect_b64 s[18:19], -1, 0
	s_cmp_eq_u32 s6, 0
	v_lshl_add_u64 v[140:141], v[0:1], 0, s[22:23]
	v_and_or_b32 v0, s24, 32, v12
	s_cselect_b64 s[20:21], -1, 0
	s_lshl_b32 s6, s7, 11
	v_lshlrev_b32_e32 v136, 1, v0
	s_and_b32 s72, s6, 0x1000
	v_lshl_add_u64 v[0:1], s[10:11], 0, v[136:137]
	s_mov_b64 s[6:7], 0x2000000
	v_lshl_add_u64 v[142:143], v[0:1], 0, s[6:7]
	v_lshlrev_b32_e32 v0, 15, v72
	v_lshlrev_b32_e32 v1, 11, v11
	v_or3_b32 v0, v9, v0, v1
	v_add_u32_e32 v144, v0, v10
	v_lshlrev_b32_e32 v0, 4, v8
	s_waitcnt vmcnt(6)
	v_and_b32_e32 v0, 0x78000, v0
	v_or3_b32 v0, v9, v0, v1
	s_add_i32 s74, 0, 0x10000
	s_add_i32 s75, 0, 0x14000
	v_or_b32_e32 v138, s24, v12
	s_ashr_i32 s73, s3, 31
	v_mov_b32_e32 v145, v137
	v_add_u32_e32 v146, v0, v10
	v_mov_b32_e32 v147, v137
	v_mov_b64_e32 v[148:149], 0xe00
	v_mov_b64_e32 v[150:151], 0xdff
	v_add_u32_e32 v160, s74, v159
	v_add_u32_e32 v161, s75, v159
	v_add_u32_e32 v162, 0, v14
	s_mov_b32 s76, 0x19ffe000
	s_mov_b32 s77, 0x1a03e000
	s_mov_b32 s78, 0x1a046000
	s_mov_b32 s79, 0x1a04e000
	s_mov_b32 s80, 0x15fff000
	s_mov_b32 s81, 0x1603f000
	s_mov_b32 s82, 0x16047000
	s_mov_b32 s83, 0x1604f000
	s_mov_b64 s[22:23], 0x5fff000
	s_mov_b32 s84, 0x5fff000
	s_mov_b64 s[24:25], 0x603f000
	s_mov_b32 s85, 0x603f000
	s_mov_b64 s[26:27], 0x6047000
	s_mov_b32 s86, 0x6047000
	s_mov_b64 s[28:29], 0x604f000
	s_mov_b32 s87, 0x604f000
	s_mov_b64 s[30:31], 0x6057000
	s_mov_b32 s88, 0x6057000
	s_mov_b32 s89, 0x12000000
	s_mov_b64 s[34:35], 0x20000
	s_mov_b32 s90, 0x20000
	s_mov_b64 s[36:37], 0x24000
	s_mov_b32 s91, 0x24000
	s_mov_b64 s[38:39], 0x28000
	s_mov_b32 s92, 0x28000
	s_mov_b64 s[42:43], 0x2c000
	s_mov_b32 s93, 0x2c000
	v_mov_b32_e32 v163, 0x3db504f3
	s_barrier
	s_waitcnt vmcnt(0)
	s_mov_b32 s100, 1
	s_mov_b32 s101, 1
	s_branch .LBB0_185

.LBB0_188:
	ds_read_b128 v[152:155], v160
	ds_read_b128 v[164:167], v160 offset:1024
	ds_read_b128 v[168:171], v160 offset:2048
	ds_read_b128 v[172:175], v160 offset:3072
	ds_read_b128 v[176:179], v161
	ds_read_b128 v[180:183], v161 offset:1024
	ds_read_b128 v[184:187], v161 offset:2048
	ds_read_b128 v[188:191], v161 offset:3072
	s_add_u32 s56, s54, 0xfffc0080
	s_addc_u32 s57, s55, -1
	s_cmp_eq_u32 s98, 12
	s_cselect_b32 s59, s47, s57
	s_cselect_b32 s58, s53, s56
	s_cselect_b32 s57, s45, s97
	s_cselect_b32 s56, s95, s96
	v_lshl_add_u64 v[156:157], s[54:55], 0, v[144:145]
	s_add_i32 m0, s64, 0xc000
	ds_read_b128 v[192:195], v162
	ds_read_b128 v[196:199], v162 offset:1024
	ds_read_b128 v[200:203], v162 offset:2048
	ds_read_b128 v[204:207], v162 offset:3072
	ds_read_b128 v[208:211], v162 offset:4096
	ds_read_b128 v[212:215], v162 offset:5120
	ds_read_b128 v[216:219], v162 offset:6144
	ds_read_b128 v[220:223], v162 offset:7168
	global_load_lds_dwordx4 v[156:157], off
	v_lshl_add_u64 v[156:157], s[54:55], 0, v[146:147]
	s_add_i32 m0, s64, 0xe000
	s_nop 0
	global_load_lds_dwordx4 v[156:157], off
	s_waitcnt vmcnt(9)
	s_cmp_eq_u32 s101, 0
	s_cbranch_scc1 .Ldf_wd0
	s_waitcnt vmcnt(8)
.Ldf_wd0:
	s_waitcnt lgkmcnt(0)
	s_barrier
	s_setprio 1
	s_waitcnt lgkmcnt(0)
	v_mfma_f32_16x16x32_bf16 v[124:127], v[152:155], v[192:195], v[124:127]
	v_mfma_f32_16x16x32_bf16 v[120:123], v[168:171], v[192:195], v[120:123]
	v_mfma_f32_16x16x32_bf16 v[116:119], v[152:155], v[200:203], v[116:119]
	v_mfma_f32_16x16x32_bf16 v[112:115], v[168:171], v[200:203], v[112:115]
	v_mfma_f32_16x16x32_bf16 v[100:103], v[152:155], v[208:211], v[100:103]
	v_mfma_f32_16x16x32_bf16 v[96:99], v[168:171], v[208:211], v[96:99]
	v_mfma_f32_16x16x32_bf16 v[84:87], v[152:155], v[216:219], v[84:87]
	v_mfma_f32_16x16x32_bf16 v[80:83], v[168:171], v[216:219], v[80:83]
	v_mfma_f32_16x16x32_bf16 v[124:127], v[164:167], v[196:199], v[124:127]
	v_mfma_f32_16x16x32_bf16 v[120:123], v[172:175], v[196:199], v[120:123]
	v_mfma_f32_16x16x32_bf16 v[116:119], v[164:167], v[204:207], v[116:119]
	v_mfma_f32_16x16x32_bf16 v[112:115], v[172:175], v[204:207], v[112:115]
	v_mfma_f32_16x16x32_bf16 v[100:103], v[164:167], v[212:215], v[100:103]
	v_mfma_f32_16x16x32_bf16 v[96:99], v[172:175], v[212:215], v[96:99]
	v_mfma_f32_16x16x32_bf16 v[84:87], v[164:167], v[220:223], v[84:87]
	v_mfma_f32_16x16x32_bf16 v[80:83], v[172:175], v[220:223], v[80:83]
	s_setprio 0
	s_setprio 1
	v_mfma_f32_16x16x32_bf16 v[108:111], v[176:179], v[192:195], v[108:111]
	v_mfma_f32_16x16x32_bf16 v[104:107], v[184:187], v[192:195], v[104:107]
	v_mfma_f32_16x16x32_bf16 v[92:95], v[176:179], v[200:203], v[92:95]
	v_mfma_f32_16x16x32_bf16 v[88:91], v[184:187], v[200:203], v[88:91]
	v_mfma_f32_16x16x32_bf16 v[76:79], v[176:179], v[208:211], v[76:79]
	v_mfma_f32_16x16x32_bf16 v[72:75], v[184:187], v[208:211], v[72:75]
	v_mfma_f32_16x16x32_bf16 v[68:71], v[176:179], v[216:219], v[68:71]
	v_mfma_f32_16x16x32_bf16 v[64:67], v[184:187], v[216:219], v[64:67]
	v_mfma_f32_16x16x32_bf16 v[108:111], v[180:183], v[196:199], v[108:111]
	v_mfma_f32_16x16x32_bf16 v[104:107], v[188:191], v[196:199], v[104:107]
	v_mfma_f32_16x16x32_bf16 v[92:95], v[180:183], v[204:207], v[92:95]
	v_mfma_f32_16x16x32_bf16 v[88:91], v[188:191], v[204:207], v[88:91]
	v_mfma_f32_16x16x32_bf16 v[76:79], v[180:183], v[212:215], v[76:79]
	v_mfma_f32_16x16x32_bf16 v[72:75], v[188:191], v[212:215], v[72:75]
	v_mfma_f32_16x16x32_bf16 v[68:71], v[180:183], v[220:223], v[68:71]
	v_mfma_f32_16x16x32_bf16 v[64:67], v[188:191], v[220:223], v[64:67]
	s_setprio 0
	s_barrier
	s_or_b32 s101, s98, s100
	s_cbranch_scc1 .Ldf_skip0
	global_store_dwordx4 v[236:237], v[232:235], off nt
.Ldf_skip0:
	s_add_i32 s99, s74, s33
	v_lshl_add_u64 v[156:157], s[56:57], 0, v[132:133]
	s_mov_b32 m0, s99
	ds_read_b128 v[192:195], v162 offset:16384
	ds_read_b128 v[196:199], v162 offset:17408
	ds_read_b128 v[200:203], v162 offset:18432
	ds_read_b128 v[204:207], v162 offset:19456
	ds_read_b128 v[208:211], v162 offset:20480
	ds_read_b128 v[212:215], v162 offset:21504
	ds_read_b128 v[216:219], v162 offset:22528
	ds_read_b128 v[220:223], v162 offset:23552
	global_load_lds_dwordx4 v[156:157], off
	s_add_i32 m0, s99, 0x2000
	s_add_u32 vcc_lo, s56, 0x40000
	v_lshl_add_u64 v[224:225], s[56:57], 0, v[128:129]
	s_addc_u32 vcc_hi, s57, 0
	s_add_i32 s99, s75, s33
	global_load_lds_dwordx4 v[224:225], off
	v_lshl_add_u64 v[226:227], vcc, 0, v[132:133]
	s_mov_b32 m0, s99
	v_lshl_add_u64 v[228:229], s[58:59], 0, v[130:131]
	global_load_lds_dwordx4 v[226:227], off
	v_lshl_add_u64 v[226:227], vcc, 0, v[128:129]
	s_add_i32 m0, s99, 0x2000
	s_nop 0
	global_load_lds_dwordx4 v[226:227], off
	v_lshl_add_u64 v[226:227], s[58:59], 0, v[134:135]
	s_mov_b32 m0, s64
	s_nop 0
	global_load_lds_dwordx4 v[226:227], off
	s_mov_b32 m0, s65
	s_nop 0
	global_load_lds_dwordx4 v[228:229], off
	s_waitcnt vmcnt(9)
	s_cmp_eq_u32 s101, 0
	s_cbranch_scc1 .Ldf_wd1
	s_waitcnt vmcnt(8)
.Ldf_wd1:
	s_waitcnt lgkmcnt(0)
	s_barrier
	s_setprio 1
	s_waitcnt lgkmcnt(0)
	v_mfma_f32_16x16x32_bf16 v[60:63], v[152:155], v[192:195], v[60:63]
	v_mfma_f32_16x16x32_bf16 v[56:59], v[168:171], v[192:195], v[56:59]
	v_mfma_f32_16x16x32_bf16 v[52:55], v[152:155], v[200:203], v[52:55]
	v_mfma_f32_16x16x32_bf16 v[48:51], v[168:171], v[200:203], v[48:51]
	v_mfma_f32_16x16x32_bf16 v[36:39], v[152:155], v[208:211], v[36:39]
	v_mfma_f32_16x16x32_bf16 v[32:35], v[168:171], v[208:211], v[32:35]
	v_mfma_f32_16x16x32_bf16 v[20:23], v[152:155], v[216:219], v[20:23]
	v_mfma_f32_16x16x32_bf16 v[16:19], v[168:171], v[216:219], v[16:19]
	v_mfma_f32_16x16x32_bf16 v[60:63], v[164:167], v[196:199], v[60:63]
	v_mfma_f32_16x16x32_bf16 v[56:59], v[172:175], v[196:199], v[56:59]
	v_mfma_f32_16x16x32_bf16 v[52:55], v[164:167], v[204:207], v[52:55]
	v_mfma_f32_16x16x32_bf16 v[48:51], v[172:175], v[204:207], v[48:51]
	v_mfma_f32_16x16x32_bf16 v[36:39], v[164:167], v[212:215], v[36:39]
	v_mfma_f32_16x16x32_bf16 v[32:35], v[172:175], v[212:215], v[32:35]
	v_mfma_f32_16x16x32_bf16 v[20:23], v[164:167], v[220:223], v[20:23]
	v_mfma_f32_16x16x32_bf16 v[16:19], v[172:175], v[220:223], v[16:19]
	s_setprio 0
	s_setprio 1
	v_mfma_f32_16x16x32_bf16 v[44:47], v[176:179], v[192:195], v[44:47]
	v_mfma_f32_16x16x32_bf16 v[40:43], v[184:187], v[192:195], v[40:43]
	v_mfma_f32_16x16x32_bf16 v[28:31], v[176:179], v[200:203], v[28:31]
	v_mfma_f32_16x16x32_bf16 v[24:27], v[184:187], v[200:203], v[24:27]
	v_mfma_f32_16x16x32_bf16 v[12:15], v[176:179], v[208:211], v[12:15]
	v_mfma_f32_16x16x32_bf16 v[8:11], v[184:187], v[208:211], v[8:11]
	v_mfma_f32_16x16x32_bf16 v[4:7], v[176:179], v[216:219], v[4:7]
	v_mfma_f32_16x16x32_bf16 v[0:3], v[184:187], v[216:219], v[0:3]
	v_mfma_f32_16x16x32_bf16 v[44:47], v[180:183], v[196:199], v[44:47]
	v_mfma_f32_16x16x32_bf16 v[40:43], v[188:191], v[196:199], v[40:43]
	v_mfma_f32_16x16x32_bf16 v[28:31], v[180:183], v[204:207], v[28:31]
	v_mfma_f32_16x16x32_bf16 v[24:27], v[188:191], v[204:207], v[24:27]
	v_mfma_f32_16x16x32_bf16 v[12:15], v[180:183], v[212:215], v[12:15]
	v_mfma_f32_16x16x32_bf16 v[8:11], v[188:191], v[212:215], v[8:11]
	v_mfma_f32_16x16x32_bf16 v[4:7], v[180:183], v[220:223], v[4:7]
	v_mfma_f32_16x16x32_bf16 v[0:3], v[188:191], v[220:223], v[0:3]
	s_setprio 0
	s_barrier
	s_or_b32 s101, s98, s100
	s_cbranch_scc1 .Ldf_skip1
	global_store_dwordx4 v[242:243], v[238:241], off nt
.Ldf_skip1:
	s_add_i32 s99, 0, 0x18000
	v_add_u32_e32 v136, s99, v159
	s_add_i32 vcc_lo, 0, 0x1c000
	ds_read_b128 v[152:155], v136
	ds_read_b128 v[164:167], v136 offset:1024
	ds_read_b128 v[168:171], v136 offset:2048
	ds_read_b128 v[172:175], v136 offset:3072
	v_add_u32_e32 v136, vcc_lo, v159
	ds_read_b128 v[176:179], v136
	ds_read_b128 v[180:183], v136 offset:1024
	ds_read_b128 v[184:187], v136 offset:2048
	ds_read_b128 v[188:191], v136 offset:3072
	s_add_u32 s58, s58, 0x40000
	s_addc_u32 s59, s59, 0
	s_mov_b32 m0, s66
	v_lshl_add_u64 v[230:231], s[58:59], 0, v[134:135]
	ds_read_b128 v[192:195], v162 offset:32768
	ds_read_b128 v[196:199], v162 offset:33792
	ds_read_b128 v[200:203], v162 offset:34816
	ds_read_b128 v[204:207], v162 offset:35840
	ds_read_b128 v[208:211], v162 offset:36864
	ds_read_b128 v[212:215], v162 offset:37888
	ds_read_b128 v[216:219], v162 offset:38912
	ds_read_b128 v[220:223], v162 offset:39936
	global_load_lds_dwordx4 v[230:231], off
	v_lshl_add_u64 v[230:231], s[58:59], 0, v[130:131]
	s_mov_b32 m0, s67
	s_nop 0
	global_load_lds_dwordx4 v[230:231], off
	s_waitcnt vmcnt(9)
	s_cmp_eq_u32 s101, 0
	s_cbranch_scc1 .Ldf_wd2
	s_waitcnt vmcnt(8)
.Ldf_wd2:
	s_waitcnt lgkmcnt(0)
	s_barrier
	s_setprio 1
	s_waitcnt lgkmcnt(0)
	v_mfma_f32_16x16x32_bf16 v[124:127], v[152:155], v[192:195], v[124:127]
	v_mfma_f32_16x16x32_bf16 v[120:123], v[168:171], v[192:195], v[120:123]
	v_mfma_f32_16x16x32_bf16 v[116:119], v[152:155], v[200:203], v[116:119]
	v_mfma_f32_16x16x32_bf16 v[112:115], v[168:171], v[200:203], v[112:115]
	v_mfma_f32_16x16x32_bf16 v[100:103], v[152:155], v[208:211], v[100:103]
	v_mfma_f32_16x16x32_bf16 v[96:99], v[168:171], v[208:211], v[96:99]
	v_mfma_f32_16x16x32_bf16 v[84:87], v[152:155], v[216:219], v[84:87]
	v_mfma_f32_16x16x32_bf16 v[80:83], v[168:171], v[216:219], v[80:83]
	v_mfma_f32_16x16x32_bf16 v[124:127], v[164:167], v[196:199], v[124:127]
	v_mfma_f32_16x16x32_bf16 v[120:123], v[172:175], v[196:199], v[120:123]
	v_mfma_f32_16x16x32_bf16 v[116:119], v[164:167], v[204:207], v[116:119]
	v_mfma_f32_16x16x32_bf16 v[112:115], v[172:175], v[204:207], v[112:115]
	v_mfma_f32_16x16x32_bf16 v[100:103], v[164:167], v[212:215], v[100:103]
	v_mfma_f32_16x16x32_bf16 v[96:99], v[172:175], v[212:215], v[96:99]
	v_mfma_f32_16x16x32_bf16 v[84:87], v[164:167], v[220:223], v[84:87]
	v_mfma_f32_16x16x32_bf16 v[80:83], v[172:175], v[220:223], v[80:83]
	s_setprio 0
	s_setprio 1
	v_mfma_f32_16x16x32_bf16 v[108:111], v[176:179], v[192:195], v[108:111]
	v_mfma_f32_16x16x32_bf16 v[104:107], v[184:187], v[192:195], v[104:107]
	v_mfma_f32_16x16x32_bf16 v[92:95], v[176:179], v[200:203], v[92:95]
	v_mfma_f32_16x16x32_bf16 v[88:91], v[184:187], v[200:203], v[88:91]
	v_mfma_f32_16x16x32_bf16 v[76:79], v[176:179], v[208:211], v[76:79]
	v_mfma_f32_16x16x32_bf16 v[72:75], v[184:187], v[208:211], v[72:75]
	v_mfma_f32_16x16x32_bf16 v[68:71], v[176:179], v[216:219], v[68:71]
	v_mfma_f32_16x16x32_bf16 v[64:67], v[184:187], v[216:219], v[64:67]
	v_mfma_f32_16x16x32_bf16 v[108:111], v[180:183], v[196:199], v[108:111]
	v_mfma_f32_16x16x32_bf16 v[104:107], v[188:191], v[196:199], v[104:107]
	v_mfma_f32_16x16x32_bf16 v[92:95], v[180:183], v[204:207], v[92:95]
	v_mfma_f32_16x16x32_bf16 v[88:91], v[188:191], v[204:207], v[88:91]
	v_mfma_f32_16x16x32_bf16 v[76:79], v[180:183], v[212:215], v[76:79]
	v_mfma_f32_16x16x32_bf16 v[72:75], v[188:191], v[212:215], v[72:75]
	v_mfma_f32_16x16x32_bf16 v[68:71], v[180:183], v[220:223], v[68:71]
	v_mfma_f32_16x16x32_bf16 v[64:67], v[188:191], v[220:223], v[64:67]
	s_setprio 0
	s_barrier
	s_or_b32 s101, s98, s100
	s_cbranch_scc1 .Ldf_skip2
	global_store_dwordx4 v[248:249], v[244:247], off nt
.Ldf_skip2:
	s_add_i32 s58, s99, s33
	v_lshl_add_u64 v[156:157], v[156:157], 0, s[16:17]
	s_mov_b32 m0, s58
	ds_read_b128 v[192:195], v162 offset:49152
	ds_read_b128 v[196:199], v162 offset:50176
	ds_read_b128 v[200:203], v162 offset:51200
	ds_read_b128 v[204:207], v162 offset:52224
	ds_read_b128 v[208:211], v162 offset:53248
	ds_read_b128 v[212:215], v162 offset:54272
	ds_read_b128 v[216:219], v162 offset:55296
	ds_read_b128 v[220:223], v162 offset:56320
	global_load_lds_dwordx4 v[156:157], off
	s_add_i32 m0, s58, 0x2000
	s_add_u32 s56, s56, 0x40080
	v_lshl_add_u64 v[156:157], v[224:225], 0, s[16:17]
	s_addc_u32 s57, s57, 0
	s_add_i32 s58, vcc_lo, s33
	global_load_lds_dwordx4 v[156:157], off
	v_lshl_add_u64 v[156:157], s[56:57], 0, v[132:133]
	s_mov_b32 m0, s58
	s_nop 0
	global_load_lds_dwordx4 v[156:157], off
	v_lshl_add_u64 v[156:157], s[56:57], 0, v[128:129]
	s_add_i32 m0, s58, 0x2000
	s_nop 0
	global_load_lds_dwordx4 v[156:157], off
	v_lshl_add_u64 v[156:157], v[226:227], 0, s[16:17]
	s_mov_b32 m0, s70
	s_nop 0
	global_load_lds_dwordx4 v[156:157], off
	v_lshl_add_u64 v[156:157], v[228:229], 0, s[16:17]
	s_mov_b32 m0, s71
	s_nop 0
	global_load_lds_dwordx4 v[156:157], off
	s_waitcnt vmcnt(9)
	s_cmp_eq_u32 s101, 0
	s_cbranch_scc1 .Ldf_wd3
	s_waitcnt vmcnt(8)
.Ldf_wd3:
	s_waitcnt lgkmcnt(0)
	s_barrier
	s_setprio 1
	s_waitcnt lgkmcnt(0)
	v_mfma_f32_16x16x32_bf16 v[60:63], v[152:155], v[192:195], v[60:63]
	v_mfma_f32_16x16x32_bf16 v[56:59], v[168:171], v[192:195], v[56:59]
	v_mfma_f32_16x16x32_bf16 v[52:55], v[152:155], v[200:203], v[52:55]
	v_mfma_f32_16x16x32_bf16 v[48:51], v[168:171], v[200:203], v[48:51]
	v_mfma_f32_16x16x32_bf16 v[36:39], v[152:155], v[208:211], v[36:39]
	v_mfma_f32_16x16x32_bf16 v[32:35], v[168:171], v[208:211], v[32:35]
	v_mfma_f32_16x16x32_bf16 v[20:23], v[152:155], v[216:219], v[20:23]
	v_mfma_f32_16x16x32_bf16 v[16:19], v[168:171], v[216:219], v[16:19]
	v_mfma_f32_16x16x32_bf16 v[60:63], v[164:167], v[196:199], v[60:63]
	v_mfma_f32_16x16x32_bf16 v[56:59], v[172:175], v[196:199], v[56:59]
	v_mfma_f32_16x16x32_bf16 v[52:55], v[164:167], v[204:207], v[52:55]
	v_mfma_f32_16x16x32_bf16 v[48:51], v[172:175], v[204:207], v[48:51]
	v_mfma_f32_16x16x32_bf16 v[36:39], v[164:167], v[212:215], v[36:39]
	v_mfma_f32_16x16x32_bf16 v[32:35], v[172:175], v[212:215], v[32:35]
	v_mfma_f32_16x16x32_bf16 v[20:23], v[164:167], v[220:223], v[20:23]
	v_mfma_f32_16x16x32_bf16 v[16:19], v[172:175], v[220:223], v[16:19]
	s_setprio 0
	s_setprio 1
	v_mfma_f32_16x16x32_bf16 v[44:47], v[176:179], v[192:195], v[44:47]
	v_mfma_f32_16x16x32_bf16 v[40:43], v[184:187], v[192:195], v[40:43]
	v_mfma_f32_16x16x32_bf16 v[28:31], v[176:179], v[200:203], v[28:31]
	v_mfma_f32_16x16x32_bf16 v[24:27], v[184:187], v[200:203], v[24:27]
	v_mfma_f32_16x16x32_bf16 v[12:15], v[176:179], v[208:211], v[12:15]
	v_mfma_f32_16x16x32_bf16 v[8:11], v[184:187], v[208:211], v[8:11]
	v_mfma_f32_16x16x32_bf16 v[4:7], v[176:179], v[216:219], v[4:7]
	v_mfma_f32_16x16x32_bf16 v[0:3], v[184:187], v[216:219], v[0:3]
	v_mfma_f32_16x16x32_bf16 v[44:47], v[180:183], v[196:199], v[44:47]
	v_mfma_f32_16x16x32_bf16 v[40:43], v[188:191], v[196:199], v[40:43]
	v_mfma_f32_16x16x32_bf16 v[28:31], v[180:183], v[204:207], v[28:31]
	v_mfma_f32_16x16x32_bf16 v[24:27], v[188:191], v[204:207], v[24:27]
	v_mfma_f32_16x16x32_bf16 v[12:15], v[180:183], v[212:215], v[12:15]
	v_mfma_f32_16x16x32_bf16 v[8:11], v[188:191], v[212:215], v[8:11]
	v_mfma_f32_16x16x32_bf16 v[4:7], v[180:183], v[220:223], v[4:7]
	v_mfma_f32_16x16x32_bf16 v[0:3], v[188:191], v[220:223], v[0:3]
	s_setprio 0
	s_barrier
	s_or_b32 s101, s98, s100
	s_cbranch_scc1 .Ldf_skip3
	global_store_dwordx4 v[254:255], v[250:253], off nt
